# speedup vs baseline: 1.0012x; 1.0012x over previous
; #define LAS __attribute__((address_space(3)))
; __device__ __forceinline__ float ret_log_gamma(int h) { return log1pf(-exp2f(-5.0f - (float)h)); }
; template <bool DEC> __device__ __forceinline__ void stage_rot128(LAS bf16_t* dst, const bf16_t* proj, int col, int tok0, const float* cosT, const float* sinT, float sc_base, float lg, int tid) {
;     u32x4 r1[2], r2[2]; f32x4 cc[2][2], sn[2][2];
; #pragma unroll
;     for (int it = 0; it < 2; ++it) { const int e = tid + it * NTHR, j = e & 127, c = e >> 7, tok = tok0 + j; const bf16_t* rp = proj + (size_t)tok * LDP + col;
;         r1[it] = *(const u32x4*)(rp + 8 * c); r2[it] = *(const u32x4*)(rp + 64 + 8 * c);
;         cc[it][0] = *(const f32x4*)(cosT + tok * 64 + 8 * c); cc[it][1] = *(const f32x4*)(cosT + tok * 64 + 8 * c + 4); sn[it][0] = *(const f32x4*)(sinT + tok * 64 + 8 * c); sn[it][1] = *(const f32x4*)(sinT + tok * 64 + 8 * c + 4); }
; __device__ __forceinline__ void retc1_unit(LAS unsigned char* lds, const bf16_t* proj, const float* cosT, const float* sinT, bf16_t* KVT, int h, int n, int tid) {
;     LAS bf16_t* Ks = (LAS bf16_t*)(lds + C_T0); LAS bf16_t* Vs = (LAS bf16_t*)(lds + C_T1);
;     const float lg = ret_log_gamma(h);
;     stage_rot128<true>(Ks, proj, C_CK + h * 128, n * 128, cosT, sinT, 0.08838834764831845f, lg, tid);
;     stage_v128(Vs, proj, C_CV + h * 128, n * 128, tid);
.LBB0_278:
	s_ashr_i32 s9, s8, 31
	s_lshr_b32 s10, s9, 25
	s_add_i32 s14, s8, s10
	s_ashr_i32 s13, s14, 7
	v_cvt_f32_i32_e32 v0, s13
	v_sub_f32_e32 v0, 0xc0a00000, v0
	v_cmp_gt_f32_e32 vcc, s22, v0
	s_and_b64 s[10:11], vcc, exec
	s_cselect_b32 s10, 0xffffffc0, 0
	v_cndmask_b32_e32 v1, 0, v209, vcc
	v_add_f32_e32 v0, v0, v1
	v_exp_f32_e32 v0, v0
	s_mul_i32 s11, s13, 0xe2000000
	v_ldexp_f32 v23, v0, s10
	v_sub_f32_e32 v2, 1.0, v23
	v_add_f32_e32 v0, -1.0, v2
	v_sub_f32_e32 v1, v0, v2
	v_add_f32_e32 v1, 1.0, v1
	v_sub_f32_e64 v0, -v23, v0
	v_add_f32_e32 v3, v0, v1
	v_frexp_mant_f32_e32 v0, v2
	v_cmp_gt_f32_e32 vcc, s24, v0
	v_cvt_f64_f32_e32 v[0:1], v2
	v_frexp_exp_i32_f64_e32 v0, v[0:1]
	v_subbrev_co_u32_e32 v8, vcc, 0, v0, vcc
	v_sub_u32_e32 v0, 0, v8
	v_ldexp_f32 v1, v2, v0
	v_add_f32_e32 v2, -1.0, v1
	v_add_f32_e32 v4, 1.0, v1
	v_ldexp_f32 v0, v3, v0
	v_add_f32_e32 v3, 1.0, v2
	v_add_f32_e32 v5, -1.0, v4
	v_sub_f32_e32 v3, v1, v3
	v_sub_f32_e32 v1, v1, v5
	v_add_f32_e32 v3, v0, v3
	v_add_f32_e32 v0, v0, v1
	v_add_f32_e32 v9, v4, v0
	v_rcp_f32_e32 v11, v9
	v_sub_f32_e32 v1, v9, v4
	v_sub_f32_e32 v10, v0, v1
	v_add_f32_e32 v1, v2, v3
	v_mul_f32_e32 v13, v1, v11
	v_sub_f32_e32 v0, v1, v2
	v_mul_f32_e32 v2, v9, v13
	v_fma_f32 v4, v13, v9, -v2
	v_fmac_f32_e32 v4, v13, v10
	v_sub_f32_e32 v12, v3, v0
	v_add_f32_e32 v0, v2, v4
	v_sub_f32_e32 v3, v1, v0
	v_pk_add_f32 v[6:7], v[0:1], v[2:3] neg_lo:[0,1] neg_hi:[0,1]
	v_mov_b32_e32 v5, v0
	v_pk_add_f32 v[0:1], v[6:7], v[4:5] neg_lo:[0,1] neg_hi:[0,1]
	v_cmp_nlt_f32_e32 vcc, 1.0, v23
	v_add_f32_e32 v1, v12, v1
	v_add_f32_e32 v0, v0, v1
	v_add_f32_e32 v1, v3, v0
	v_mul_f32_e32 v12, v11, v1
	v_mul_f32_e32 v2, v9, v12
	v_fma_f32 v4, v12, v9, -v2
	v_fmac_f32_e32 v4, v12, v10
	v_sub_f32_e32 v3, v3, v1
	v_add_f32_e32 v9, v0, v3
	v_add_f32_e32 v0, v2, v4
	v_sub_f32_e32 v3, v1, v0
	v_pk_add_f32 v[6:7], v[0:1], v[2:3] neg_lo:[0,1] neg_hi:[0,1]
	v_mov_b32_e32 v5, v0
	v_pk_add_f32 v[0:1], v[6:7], v[4:5] neg_lo:[0,1] neg_hi:[0,1]
	s_and_b32 s10, s14, 0xffffff80
	v_add_f32_e32 v1, v9, v1
	v_add_f32_e32 v0, v0, v1
	v_add_f32_e32 v1, v13, v12
	v_add_f32_e32 v0, v3, v0
	v_sub_f32_e32 v2, v1, v13
	v_mul_f32_e32 v0, v11, v0
	v_sub_f32_e32 v2, v12, v2
	v_add_f32_e32 v2, v2, v0
	v_add_f32_e32 v4, v1, v2
	v_mul_f32_e32 v5, v4, v4
	v_fmamk_f32 v0, v5, 0x3e9b6dac, v206
	v_fmaak_f32 v171, v5, v0, 0x3f2aaada
	v_cvt_f32_i32_e32 v0, v8
	v_sub_f32_e32 v1, v4, v1
	v_sub_f32_e32 v1, v2, v1
	v_ldexp_f32 v6, v1, 1
	v_mul_f32_e32 v1, v4, v5
	v_ldexp_f32 v3, v4, 1
	v_pk_mul_f32 v[4:5], v[0:1], v[170:171]
	s_mov_b64 s[14:15], 0x2f00
	v_fma_f32 v2, v0, s20, -v4
	v_fmac_f32_e32 v2, 0xb102e308, v0
	v_pk_add_f32 v[0:1], v[4:5], v[2:3]
	s_nop 0
	v_sub_f32_e32 v3, v1, v3
	v_sub_f32_e32 v3, v5, v3
	v_add_f32_e32 v7, v6, v3
	v_mov_b32_e32 v6, v4
	v_pk_add_f32 v[4:5], v[0:1], v[4:5] neg_lo:[0,1] neg_hi:[0,1]
	v_pk_add_f32 v[8:9], v[0:1], v[6:7]
	v_mov_b32_e32 v3, v0
	v_mov_b32_e32 v5, v9
	v_pk_add_f32 v[10:11], v[2:3], v[4:5] neg_lo:[0,1] neg_hi:[0,1]
	v_pk_add_f32 v[2:3], v[2:3], v[4:5]
	v_mov_b32_e32 v14, v1
	v_pk_add_f32 v[4:5], v[2:3], v[0:1] op_sel:[1,0] op_sel_hi:[0,1] neg_lo:[0,1] neg_hi:[0,1]
	v_pk_add_f32 v[12:13], v[8:9], v[4:5] op_sel_hi:[1,0] neg_lo:[0,1] neg_hi:[0,1]
	v_mov_b32_e32 v8, v9
	v_mov_b32_e32 v9, v3
	v_mov_b32_e32 v15, v4
	v_pk_add_f32 v[4:5], v[8:9], v[14:15] neg_lo:[0,1] neg_hi:[0,1]
	v_mov_b32_e32 v6, v7
	v_mov_b32_e32 v7, v0
	v_pk_add_f32 v[0:1], v[6:7], v[4:5] neg_lo:[0,1] neg_hi:[0,1]
	v_mov_b32_e32 v12, v10
	v_pk_add_f32 v[4:5], v[12:13], v[0:1]
	v_mov_b32_e32 v11, v3
	v_pk_add_f32 v[6:7], v[4:5], v[4:5] op_sel:[0,1] op_sel_hi:[1,0]
	v_lshlrev_b64 v[14:15], 1, v[16:17]
	v_pk_add_f32 v[2:3], v[2:3], v[6:7] op_sel:[1,0] op_sel_hi:[0,1]
	v_mov_b32_e32 v5, v2
	v_pk_add_f32 v[8:9], v[4:5], v[10:11] neg_lo:[0,1] neg_hi:[0,1]
	v_mov_b32_e32 v1, v6
	v_sub_f32_e32 v3, v4, v8
	v_pk_add_f32 v[0:1], v[0:1], v[8:9] neg_lo:[0,1] neg_hi:[0,1]
	v_sub_f32_e32 v3, v10, v3
	v_add_f32_e32 v0, v0, v3
	v_add_f32_e32 v0, v0, v1
	v_add_f32_e32 v0, v2, v0
	v_cndmask_b32_e32 v0, v210, v0, vcc
	v_cmp_neq_f32_e32 vcc, 1.0, v23
	s_nop 1
	v_cndmask_b32_e32 v0, v211, v0, vcc
	v_cmp_gt_f32_e32 vcc, s25, v23
	s_nop 1
	v_cndmask_b32_e64 v8, v0, -v23, vcc
	v_add_u32_e32 v0, s11, v35
	v_ashrrev_i32_e32 v1, 31, v0
	s_ashr_i32 s11, s10, 31
	v_lshl_add_u64 v[0:1], s[40:41], 0, v[0:1]
	s_lshl_b64 s[10:11], s[10:11], 1
	v_lshl_add_u64 v[0:1], v[0:1], 0, s[10:11]
	v_lshl_add_u64 v[4:5], v[0:1], 0, s[14:15]
	s_mov_b64 s[14:15], 0x2f80
	v_lshl_add_u64 v[6:7], v[0:1], 0, s[14:15]
	s_lshl_b32 s14, s13, 20
	v_subrev_u32_e32 v0, s14, v36
	v_ashrrev_i32_e32 v1, 31, v0
	v_lshlrev_b64 v[0:1], 2, v[0:1]
	v_lshl_add_u64 v[10:11], v[4:5], 0, v[14:15]
	v_lshl_add_u64 v[14:15], v[6:7], 0, v[14:15]
	v_lshl_add_u64 v[2:3], s[4:5], 0, v[0:1]
	v_lshl_add_u64 v[0:1], s[6:7], 0, v[0:1]
	global_load_dwordx4 v[10:13], v[10:11], off
	v_mul_f32_e32 v8, v8, v28
	global_load_dwordx4 v[42:45], v[14:15], off
	v_lshlrev_b64 v[14:15], 2, v[16:17]
	v_lshl_add_u64 v[24:25], v[2:3], 0, v[14:15]
	v_lshl_add_u64 v[14:15], v[0:1], 0, v[14:15]
	global_load_dwordx4 v[46:49], v[24:25], off offset:16
	global_load_dwordx4 v[50:53], v[24:25], off
	global_load_dwordx4 v[54:57], v[14:15], off offset:16
	global_load_dwordx4 v[58:61], v[14:15], off
	v_lshlrev_b64 v[14:15], 1, v[18:19]
	v_lshl_add_u64 v[4:5], v[4:5], 0, v[14:15]
	global_load_dwordx4 v[62:65], v[4:5], off
	v_lshl_add_u64 v[4:5], v[6:7], 0, v[14:15]
	v_lshlrev_b64 v[14:15], 2, v[18:19]
	v_lshl_add_u64 v[2:3], v[2:3], 0, v[14:15]
	v_lshl_add_u64 v[14:15], v[0:1], 0, v[14:15]
	global_load_dwordx4 v[4:7], v[4:5], off
	s_nop 0
	global_load_dwordx4 v[66:69], v[2:3], off offset:16
	global_load_dwordx4 v[70:73], v[2:3], off
	s_nop 0
	global_load_dwordx4 v[0:3], v[14:15], off offset:16
	global_load_dwordx4 v[74:77], v[14:15], off
	v_mul_f32_e32 v8, 0x3fb8aa3b, v8
	v_exp_f32_e32 v8, v8
	s_add_u32 s10, s40, s10
	s_addc_u32 s11, s41, s11
	v_mov_b32_e32 v236, v22
	v_mov_b32_e32 v237, v32
	v_lshl_add_u64 v[236:237], s[10:11], 0, v[236:237]
	s_mov_b64 s[10:11], 0x3700
	v_lshl_add_u64 v[238:239], v[236:237], 0, s[10:11]
	s_lshl_b32 s10, s13, 14
	s_sub_i32 s13, s12, s10
	v_add_u32_e32 v236, s13, v26
	v_mad_i64_i32 v[240:241], s[10:11], v236, s23, v[238:239]
	v_add_u32_e32 v236, s13, v27
	global_load_dwordx4 v[220:223], v[240:241], off
	v_mad_i64_i32 v[240:241], s[10:11], v236, s23, v[238:239]
	v_add_u32_e32 v236, s13, v31
	global_load_dwordx4 v[224:227], v[240:241], off
	v_mad_i64_i32 v[240:241], s[10:11], v236, s23, v[238:239]
	v_add_u32_e32 v236, s13, v33
	global_load_dwordx4 v[228:231], v[240:241], off
	v_mad_i64_i32 v[240:241], s[10:11], v236, s23, v[238:239]
	global_load_dwordx4 v[232:235], v[240:241], off
	v_add_u32_e32 v36, s0, v36
	s_waitcnt vmcnt(15)
; #define LAS __attribute__((address_space(3)))
; __device__ __forceinline__ void unpack8(const u32x4 r, float (&v)[8]) { v[0] = bf_lo(r.x); v[1] = bf_hi(r.x); v[2] = bf_lo(r.y); v[3] = bf_hi(r.y); v[4] = bf_lo(r.z); v[5] = bf_hi(r.z); v[6] = bf_lo(r.w); v[7] = bf_hi(r.w); }
; __device__ __forceinline__ u32x4 pack8(const float (&v)[8]) { u32x4 w; w.x = cvt_pk_bf16(v[0], v[1]); w.y = cvt_pk_bf16(v[2], v[3]); w.z = cvt_pk_bf16(v[4], v[5]); w.w = cvt_pk_bf16(v[6], v[7]); return w; }
; template <bool DEC> __device__ __forceinline__ void stage_rot128(LAS bf16_t* dst, const bf16_t* proj, int col, int tok0, const float* cosT, const float* sinT, float sc_base, float lg, int tid) {
;     ...
;     for (int it = 0; it < 2; ++it) { const int e = tid + it * NTHR, j = e & 127, c = e >> 7;
;         float x1[8], x2[8]; unpack8(r1[it], x1); unpack8(r2[it], x2);
;         float sc = sc_base; if (DEC) sc *= __expf(lg * (float)(127 - j));
;         float o1[8], o2[8];
; #pragma unroll
;         for (int t = 0; t < 8; ++t) { const float cs = cc[it][t >> 2][t & 3], sv = sn[it][t >> 2][t & 3]; o1[t] = (x1[t] * cs - x2[t] * sv) * sc; o2[t] = (x2[t] * cs + x1[t] * sv) * sc; }
;         *(LAS u32x4*)(dst + j * CP + 8 * c) = pack8(o1); *(LAS u32x4*)(dst + j * CP + 64 + 8 * c) = pack8(o2); }
; }
; __device__ __forceinline__ void stage_v128(LAS bf16_t* dst, const bf16_t* proj, int col, int tok0, int tid) {
;     u32x4 raw[4];
; #pragma unroll
;     for (int it = 0; it < 4; ++it) { const int e = tid + it * NTHR, j = e >> 4, c = e & 15; raw[it] = *(const u32x4*)(proj + (size_t)(tok0 + j) * LDP + col + 8 * c); }
; #pragma unroll
;     for (int it = 0; it < 4; ++it) { const int e = tid + it * NTHR, j = e >> 4, c = e & 15; *(LAS u32x4*)(dst + j * CP + 8 * c) = raw[it]; }
; }
	v_lshlrev_b32_e32 v14, 16, v10
	s_waitcnt vmcnt(14)
	v_lshlrev_b32_e32 v15, 16, v42
	s_waitcnt vmcnt(13)
	v_mov_b32_e32 v9, v48
	s_waitcnt vmcnt(12)
	v_mov_b32_e32 v24, v50
	s_waitcnt vmcnt(10)
	v_mov_b32_e32 v25, v58
	v_mov_b32_e32 v78, v58
	v_mov_b32_e32 v79, v50
	v_pk_mul_f32 v[24:25], v[24:25], v[14:15]
	v_pk_mul_f32 v[14:15], v[78:79], v[14:15]
	v_and_b32_e32 v79, 0xffff0000, v42
	v_and_b32_e32 v78, 0xffff0000, v10
	v_mov_b32_e32 v58, v51
	v_mov_b32_e32 v50, v59
	v_pk_mul_f32 v[80:81], v[58:59], v[78:79]
	v_pk_mul_f32 v[50:51], v[50:51], v[78:79]
	v_lshlrev_b32_e32 v59, 16, v43
	v_lshlrev_b32_e32 v58, 16, v11
	v_mov_b32_e32 v78, v52
	v_mov_b32_e32 v79, v60
	v_mov_b32_e32 v82, v60
	v_mov_b32_e32 v83, v52
	v_and_b32_e32 v43, 0xffff0000, v43
	v_and_b32_e32 v42, 0xffff0000, v11
	v_mov_b32_e32 v60, v53
	v_mov_b32_e32 v52, v61
	v_pk_mul_f32 v[78:79], v[78:79], v[58:59]
	v_pk_mul_f32 v[58:59], v[82:83], v[58:59]
	v_pk_mul_f32 v[10:11], v[60:61], v[42:43]
	v_pk_mul_f32 v[42:43], v[52:53], v[42:43]
	v_lshlrev_b32_e32 v53, 16, v44
	v_lshlrev_b32_e32 v52, 16, v12
	v_mov_b32_e32 v60, v46
	v_mov_b32_e32 v61, v54
	v_mov_b32_e32 v82, v54
	v_mov_b32_e32 v83, v46
	v_pk_mul_f32 v[60:61], v[60:61], v[52:53]
	v_pk_mul_f32 v[52:53], v[82:83], v[52:53]
	v_and_b32_e32 v83, 0xffff0000, v44
	v_and_b32_e32 v82, 0xffff0000, v12
	v_mov_b32_e32 v54, v47
	v_pk_mul_f32 v[84:85], v[54:55], v[82:83]
	v_mov_b32_e32 v46, v55
	v_lshlrev_b32_e32 v55, 16, v13
	v_mov_b32_e32 v163, v55
	v_pk_mul_f32 v[46:47], v[46:47], v[82:83]
	v_pk_mul_f32 v[82:83], v[8:9], v[162:163]
	v_sub_f32_e32 v8, v24, v25
	v_mul_f32_e32 v12, v82, v8
	v_add_f32_e32 v8, v15, v14
	v_mul_f32_e32 v14, v82, v8
	v_sub_f32_e32 v8, v80, v81
	v_mul_f32_e32 v15, v82, v8
	v_add_f32_e32 v8, v51, v50
	v_mul_f32_e32 v23, v82, v8
	v_sub_f32_e32 v8, v78, v79
	v_mul_f32_e32 v24, v82, v8
	v_add_f32_e32 v8, v59, v58
	v_mul_f32_e32 v25, v82, v8
	v_sub_f32_e32 v8, v10, v11
	v_mul_f32_e32 v44, v82, v8
	v_add_f32_e32 v8, v43, v42
	v_mul_f32_e32 v42, v82, v8
	v_sub_f32_e32 v8, v60, v61
	v_mul_f32_e32 v43, v82, v8
	v_add_f32_e32 v8, v53, v52
	v_mul_f32_e32 v50, v82, v8
	v_sub_f32_e32 v8, v84, v85
	v_lshlrev_b32_e32 v54, 16, v45
	v_mul_f32_e32 v51, v82, v8
	v_add_f32_e32 v8, v47, v46
	v_mul_f32_e32 v46, v82, v8
	v_fma_f32 v8, -v56, v54, v83
	v_mul_f32_e32 v47, v82, v8
	v_mov_b32_e32 v8, v48
	v_mov_b32_e32 v9, v56
	v_pk_mul_f32 v[8:9], v[8:9], v[54:55]
	v_mov_b32_e32 v56, v49
	v_add_f32_e32 v8, v8, v9
	v_mul_f32_e32 v52, v82, v8
	v_and_b32_e32 v9, 0xffff0000, v45
	v_and_b32_e32 v8, 0xffff0000, v13
	v_pk_mul_f32 v[10:11], v[56:57], v[8:9]
	v_mov_b32_e32 v48, v57
	v_sub_f32_e32 v10, v10, v11
	v_pk_mul_f32 v[8:9], v[48:49], v[8:9]
	v_mul_f32_e32 v11, v82, v10
	v_add_f32_e32 v8, v9, v8
	v_mul_f32_e32 v13, v82, v8
	v_cvt_pk_bf16_f32 v8, v12, v15
	v_cvt_pk_bf16_f32 v9, v24, v44
	v_cvt_pk_bf16_f32 v10, v43, v51
	v_cvt_pk_bf16_f32 v11, v47, v11
	ds_write_b128 v29, v[8:11]
	v_cvt_pk_bf16_f32 v8, v14, v23
	v_cvt_pk_bf16_f32 v9, v25, v42
	v_cvt_pk_bf16_f32 v10, v50, v46
	v_cvt_pk_bf16_f32 v11, v52, v13
	ds_write_b128 v29, v[8:11] offset:128
	s_waitcnt vmcnt(8)
	v_lshlrev_b32_e32 v9, 16, v4
	v_lshlrev_b32_e32 v8, 16, v62
	s_waitcnt vmcnt(6)
	v_mov_b32_e32 v10, v70
	s_waitcnt vmcnt(4)
	v_mov_b32_e32 v11, v74
	v_pk_mul_f32 v[10:11], v[10:11], v[8:9]
	s_nop 0
	v_sub_f32_e32 v10, v10, v11
	v_mul_f32_e32 v12, v82, v10
	v_mov_b32_e32 v10, v74
	v_mov_b32_e32 v11, v70
	v_pk_mul_f32 v[8:9], v[10:11], v[8:9]
	v_mov_b32_e32 v74, v71
	v_add_f32_e32 v8, v9, v8
	v_mul_f32_e32 v13, v82, v8
	v_and_b32_e32 v9, 0xffff0000, v4
	v_and_b32_e32 v8, 0xffff0000, v62
	v_pk_mul_f32 v[10:11], v[74:75], v[8:9]
	v_mov_b32_e32 v70, v75
	v_sub_f32_e32 v4, v10, v11
	v_pk_mul_f32 v[8:9], v[70:71], v[8:9]
	v_mul_f32_e32 v14, v82, v4
	v_add_f32_e32 v4, v9, v8
	v_lshlrev_b32_e32 v9, 16, v5
	v_lshlrev_b32_e32 v8, 16, v63
	v_mov_b32_e32 v10, v72
	v_mov_b32_e32 v11, v76
	v_pk_mul_f32 v[10:11], v[10:11], v[8:9]
	v_mul_f32_e32 v15, v82, v4
	v_sub_f32_e32 v4, v10, v11
	v_mov_b32_e32 v10, v76
	v_mov_b32_e32 v11, v72
	v_pk_mul_f32 v[8:9], v[10:11], v[8:9]
	v_mul_f32_e32 v23, v82, v4
	v_add_f32_e32 v4, v9, v8
	v_mul_f32_e32 v10, v82, v4
	v_and_b32_e32 v5, 0xffff0000, v5
	v_and_b32_e32 v4, 0xffff0000, v63
	v_mov_b32_e32 v76, v73
	v_mov_b32_e32 v72, v77
	v_pk_mul_f32 v[8:9], v[76:77], v[4:5]
	v_pk_mul_f32 v[4:5], v[72:73], v[4:5]
	v_sub_f32_e32 v8, v8, v9
	v_add_f32_e32 v4, v5, v4
	v_mul_f32_e32 v11, v82, v8
	v_mul_f32_e32 v24, v82, v4
	v_lshlrev_b32_e32 v5, 16, v6
	v_lshlrev_b32_e32 v4, 16, v64
	v_mov_b32_e32 v8, v66
	v_mov_b32_e32 v9, v0
	v_pk_mul_f32 v[8:9], v[8:9], v[4:5]
	s_nop 0
	v_sub_f32_e32 v8, v8, v9
	v_mul_f32_e32 v25, v82, v8
	v_mov_b32_e32 v8, v0
	v_mov_b32_e32 v9, v66
	v_pk_mul_f32 v[4:5], v[8:9], v[4:5]
	v_mov_b32_e32 v66, v1
	v_add_f32_e32 v0, v5, v4
	v_mul_f32_e32 v42, v82, v0
	v_and_b32_e32 v5, 0xffff0000, v6
	v_and_b32_e32 v4, 0xffff0000, v64
	v_mov_b32_e32 v0, v67
	v_pk_mul_f32 v[8:9], v[0:1], v[4:5]
	s_nop 0
	v_sub_f32_e32 v0, v8, v9
	v_mul_f32_e32 v6, v82, v0
	v_pk_mul_f32 v[0:1], v[66:67], v[4:5]
	v_mov_b32_e32 v4, v68
	v_add_f32_e32 v0, v1, v0
	v_mul_f32_e32 v8, v82, v0
	v_lshlrev_b32_e32 v1, 16, v7
	v_lshlrev_b32_e32 v0, 16, v65
	v_mov_b32_e32 v5, v2
	v_pk_mul_f32 v[4:5], v[4:5], v[0:1]
	s_nop 0
	v_sub_f32_e32 v4, v4, v5
	v_mul_f32_e32 v9, v82, v4
	v_mov_b32_e32 v4, v2
	v_mov_b32_e32 v5, v68
	v_pk_mul_f32 v[0:1], v[4:5], v[0:1]
	v_mov_b32_e32 v2, v69
	v_add_f32_e32 v0, v1, v0
	v_mul_f32_e32 v43, v82, v0
	v_and_b32_e32 v1, 0xffff0000, v7
	v_and_b32_e32 v0, 0xffff0000, v65
	v_mov_b32_e32 v68, v3
	v_pk_mul_f32 v[4:5], v[2:3], v[0:1]
	v_pk_mul_f32 v[0:1], v[68:69], v[0:1]
	v_sub_f32_e32 v2, v4, v5
	v_add_f32_e32 v0, v1, v0
	v_mul_f32_e32 v5, v82, v0
	v_cvt_pk_bf16_f32 v0, v12, v14
	v_cvt_pk_bf16_f32 v1, v23, v11
	v_mul_f32_e32 v4, v82, v2
	v_cvt_pk_bf16_f32 v2, v25, v6
	v_cvt_pk_bf16_f32 v3, v9, v4
	ds_write_b128 v30, v[0:3]
	v_cvt_pk_bf16_f32 v0, v13, v15
	v_cvt_pk_bf16_f32 v1, v10, v24
	v_mov_b32_e32 v23, v32
	v_cvt_pk_bf16_f32 v2, v42, v8
	v_cvt_pk_bf16_f32 v3, v43, v5
	ds_write_b128 v30, v[0:3] offset:128
	s_waitcnt vmcnt(0)
	ds_write_b128 v37, v[220:223] offset:34816
	ds_write_b128 v38, v[224:227] offset:34816
	ds_write_b128 v39, v[228:231] offset:34816
	ds_write_b128 v40, v[232:235] offset:34816
	s_waitcnt lgkmcnt(0)
	s_barrier
; #define LAS __attribute__((address_space(3)))
; __device__ __forceinline__ unsigned f2bf(float f) { unsigned u = __builtin_bit_cast(unsigned, f); return (u + 0x7fffu + ((u >> 16) & 1u)) >> 16; }
; __device__ __forceinline__ f32x4 mfma16(bf16x8 a, bf16x8 b, f32x4 c) { return __builtin_amdgcn_mfma_f32_16x16x32_bf16(a, b, c, 0, 0, 0); }
; __device__ __forceinline__ bf16x8 cat44(s16x4 lo, s16x4 hi) { return __builtin_shufflevector(lo, hi, 0, 1, 2, 3, 4, 5, 6, 7); }
; __device__ __forceinline__ s16x4 lds_tr(const LAS bf16_t* p) { return __builtin_bit_cast(s16x4, __builtin_amdgcn_ds_read_tr16_b64_v4i16((LAS v4i16_t*)p)); }
; __device__ __forceinline__ void retc1_unit(LAS unsigned char* lds, const bf16_t* proj, const float* cosT, const float* sinT, bf16_t* KVT, int h, int n, int tid) {
;     ...
;     const int w = tid >> 6, lane = tid & 63, l15 = lane & 15, quad = lane >> 4;
;     const int trow = quad * 8 + (l15 >> 2), tcol = 4 * (l15 & 3);
;     bf16x8 af[4];
; #pragma unroll
;     for (int ks = 0; ks < 4; ++ks) { const LAS bf16_t* vp = Vs + (32 * ks + trow) * CP + 16 * w + tcol; af[ks] = cat44(lds_tr(vp), lds_tr(vp + 4 * CP)); }
;     bf16_t* outp = KVT + ((size_t)(h * 128 + n) * 128 + 16 * w + quad * 4) * 128 + l15;
; #pragma unroll
;     for (int dt = 0; dt < 8; ++dt) { f32x4 acc = (f32x4){0.f, 0.f, 0.f, 0.f};
; #pragma unroll
;         for (int ks = 0; ks < 4; ++ks) { const LAS bf16_t* kp = Ks + (32 * ks + trow) * CP + 16 * dt + tcol; const bf16x8 b = cat44(lds_tr(kp), lds_tr(kp + 4 * CP)); acc = mfma16(af[ks], b, acc); }
; #pragma unroll
;         for (int j = 0; j < 4; ++j) outp[(size_t)j * 128 + 16 * dt] = (bf16_t)f2bf(acc[j]); }
	ds_read_b64_tr_b16 v[12:13], v41 offset:34816
	ds_read_b64_tr_b16 v[14:15], v41 offset:35904
	ds_read_b64_tr_b16 v[8:9], v41 offset:43520
	ds_read_b64_tr_b16 v[10:11], v41 offset:44608
	ds_read_b64_tr_b16 v[4:5], v41 offset:52224
	ds_read_b64_tr_b16 v[6:7], v41 offset:53312
	ds_read_b64_tr_b16 v[0:1], v41 offset:60928
	ds_read_b64_tr_b16 v[2:3], v41 offset:62016
	ds_read_b64_tr_b16 v[42:43], v34
	ds_read_b64_tr_b16 v[44:45], v34 offset:1088
	ds_read_b64_tr_b16 v[46:47], v34 offset:8704
	ds_read_b64_tr_b16 v[48:49], v34 offset:9792
	s_waitcnt lgkmcnt(2)
	v_mfma_f32_16x16x32_bf16 v[42:45], v[42:45], v[12:15], 0
	s_lshl_b64 s[10:11], s[8:9], 15
	v_lshl_add_u64 v[24:25], v[20:21], 0, s[10:11]
	v_and_b32_e32 v238, 15, v207
	v_lshrrev_b32_e32 v239, 4, v207
	v_lshlrev_b32_e32 v239, 2, v239
	v_sub_u32_e32 v238, v238, v239
	v_mul_i32_i24_e32 v238, 0xfe, v238
	v_ashrrev_i32_e32 v239, 31, v238
	v_lshl_add_u64 v[240:241], v[24:25], 0, v[238:239]
	s_add_i32 s8, s8, s16
	s_waitcnt lgkmcnt(0)
	v_mfma_f32_16x16x32_bf16 v[42:45], v[46:49], v[8:11], v[42:45]
	ds_read_b64_tr_b16 v[46:47], v34 offset:17408
	ds_read_b64_tr_b16 v[48:49], v34 offset:18496
	s_add_i32 s12, s12, s17
	s_mul_i32 s9, s16, 0x3c0000
	s_waitcnt lgkmcnt(0)
	v_mfma_f32_16x16x32_bf16 v[42:45], v[46:49], v[4:7], v[42:45]
	ds_read_b64_tr_b16 v[46:47], v34 offset:26112
	ds_read_b64_tr_b16 v[48:49], v34 offset:27200
	v_add_u32_e32 v35, s9, v35
	s_cmpk_lt_i32 s8, 0x400
	s_waitcnt lgkmcnt(0)
	v_mfma_f32_16x16x32_bf16 v[42:45], v[46:49], v[0:3], v[42:45]
	s_nop 7
	v_cvt_pk_bf16_f32 v236, v42, v43
	v_cvt_pk_bf16_f32 v237, v44, v45
	global_store_dwordx2 v[240:241], v[236:237], off
	ds_read_b64_tr_b16 v[42:43], v34 offset:32
	ds_read_b64_tr_b16 v[44:45], v34 offset:1120
	ds_read_b64_tr_b16 v[46:47], v34 offset:8736
	ds_read_b64_tr_b16 v[48:49], v34 offset:9824
	s_waitcnt lgkmcnt(2)
	v_mfma_f32_16x16x32_bf16 v[42:45], v[42:45], v[12:15], 0
	s_waitcnt lgkmcnt(0)
	v_mfma_f32_16x16x32_bf16 v[42:45], v[46:49], v[8:11], v[42:45]
	ds_read_b64_tr_b16 v[46:47], v34 offset:17440
	ds_read_b64_tr_b16 v[48:49], v34 offset:18528
	s_waitcnt lgkmcnt(0)
	v_mfma_f32_16x16x32_bf16 v[42:45], v[46:49], v[4:7], v[42:45]
	ds_read_b64_tr_b16 v[46:47], v34 offset:26144
	ds_read_b64_tr_b16 v[48:49], v34 offset:27232
	s_waitcnt lgkmcnt(0)
	v_mfma_f32_16x16x32_bf16 v[42:45], v[46:49], v[0:3], v[42:45]
	s_nop 7
	v_cvt_pk_bf16_f32 v236, v42, v43
	v_cvt_pk_bf16_f32 v237, v44, v45
	global_store_dwordx2 v[240:241], v[236:237], off offset:32
	ds_read_b64_tr_b16 v[42:43], v34 offset:64
	ds_read_b64_tr_b16 v[44:45], v34 offset:1152
	ds_read_b64_tr_b16 v[46:47], v34 offset:8768
	ds_read_b64_tr_b16 v[48:49], v34 offset:9856
	s_waitcnt lgkmcnt(2)
	v_mfma_f32_16x16x32_bf16 v[42:45], v[42:45], v[12:15], 0
	s_waitcnt lgkmcnt(0)
	v_mfma_f32_16x16x32_bf16 v[42:45], v[46:49], v[8:11], v[42:45]
	ds_read_b64_tr_b16 v[46:47], v34 offset:17472
	ds_read_b64_tr_b16 v[48:49], v34 offset:18560
	s_waitcnt lgkmcnt(0)
	v_mfma_f32_16x16x32_bf16 v[42:45], v[46:49], v[4:7], v[42:45]
	ds_read_b64_tr_b16 v[46:47], v34 offset:26176
	ds_read_b64_tr_b16 v[48:49], v34 offset:27264
	s_waitcnt lgkmcnt(0)
	v_mfma_f32_16x16x32_bf16 v[42:45], v[46:49], v[0:3], v[42:45]
	s_nop 7
	v_cvt_pk_bf16_f32 v236, v42, v43
	v_cvt_pk_bf16_f32 v237, v44, v45
	global_store_dwordx2 v[240:241], v[236:237], off offset:64
	ds_read_b64_tr_b16 v[42:43], v34 offset:96
	ds_read_b64_tr_b16 v[44:45], v34 offset:1184
	ds_read_b64_tr_b16 v[46:47], v34 offset:8800
	ds_read_b64_tr_b16 v[48:49], v34 offset:9888
	s_waitcnt lgkmcnt(2)
	v_mfma_f32_16x16x32_bf16 v[42:45], v[42:45], v[12:15], 0
	s_waitcnt lgkmcnt(0)
	v_mfma_f32_16x16x32_bf16 v[42:45], v[46:49], v[8:11], v[42:45]
	ds_read_b64_tr_b16 v[46:47], v34 offset:17504
	ds_read_b64_tr_b16 v[48:49], v34 offset:18592
	s_waitcnt lgkmcnt(0)
; #define LAS __attribute__((address_space(3)))
; __device__ __forceinline__ unsigned f2bf(float f) { unsigned u = __builtin_bit_cast(unsigned, f); return (u + 0x7fffu + ((u >> 16) & 1u)) >> 16; }
; __device__ __forceinline__ void lds_barrier() { asm volatile("s_waitcnt lgkmcnt(0)\n\ts_barrier" ::: "memory"); }
; __device__ __forceinline__ f32x4 mfma16(bf16x8 a, bf16x8 b, f32x4 c) { return __builtin_amdgcn_mfma_f32_16x16x32_bf16(a, b, c, 0, 0, 0); }
; __device__ __forceinline__ bf16x8 cat44(s16x4 lo, s16x4 hi) { return __builtin_shufflevector(lo, hi, 0, 1, 2, 3, 4, 5, 6, 7); }
; __device__ __forceinline__ s16x4 lds_tr(const LAS bf16_t* p) { return __builtin_bit_cast(s16x4, __builtin_amdgcn_ds_read_tr16_b64_v4i16((LAS v4i16_t*)p)); }
; __device__ __forceinline__ void retc1_unit(LAS unsigned char* lds, const bf16_t* proj, const float* cosT, const float* sinT, bf16_t* KVT, int h, int n, int tid) {
;     ...
;     for (int dt = 0; dt < 8; ++dt) { f32x4 acc = (f32x4){0.f, 0.f, 0.f, 0.f};
; #pragma unroll
;         for (int ks = 0; ks < 4; ++ks) { const LAS bf16_t* kp = Ks + (32 * ks + trow) * CP + 16 * dt + tcol; const bf16x8 b = cat44(lds_tr(kp), lds_tr(kp + 4 * CP)); acc = mfma16(af[ks], b, acc); }
; #pragma unroll
;         for (int j = 0; j < 4; ++j) outp[(size_t)j * 128 + 16 * dt] = (bf16_t)f2bf(acc[j]); }
;     lds_barrier();
	v_mfma_f32_16x16x32_bf16 v[42:45], v[46:49], v[4:7], v[42:45]
	ds_read_b64_tr_b16 v[46:47], v34 offset:26208
	ds_read_b64_tr_b16 v[48:49], v34 offset:27296
	s_waitcnt lgkmcnt(0)
	v_mfma_f32_16x16x32_bf16 v[42:45], v[46:49], v[0:3], v[42:45]
	s_nop 7
	v_cvt_pk_bf16_f32 v236, v42, v43
	v_cvt_pk_bf16_f32 v237, v44, v45
	global_store_dwordx2 v[240:241], v[236:237], off offset:96
	ds_read_b64_tr_b16 v[42:43], v34 offset:128
	ds_read_b64_tr_b16 v[44:45], v34 offset:1216
	ds_read_b64_tr_b16 v[46:47], v34 offset:8832
	ds_read_b64_tr_b16 v[48:49], v34 offset:9920
	s_waitcnt lgkmcnt(2)
	v_mfma_f32_16x16x32_bf16 v[42:45], v[42:45], v[12:15], 0
	s_waitcnt lgkmcnt(0)
	v_mfma_f32_16x16x32_bf16 v[42:45], v[46:49], v[8:11], v[42:45]
	ds_read_b64_tr_b16 v[46:47], v34 offset:17536
	ds_read_b64_tr_b16 v[48:49], v34 offset:18624
	s_waitcnt lgkmcnt(0)
	v_mfma_f32_16x16x32_bf16 v[42:45], v[46:49], v[4:7], v[42:45]
	ds_read_b64_tr_b16 v[46:47], v34 offset:26240
	ds_read_b64_tr_b16 v[48:49], v34 offset:27328
	s_waitcnt lgkmcnt(0)
	v_mfma_f32_16x16x32_bf16 v[42:45], v[46:49], v[0:3], v[42:45]
	s_nop 7
	v_cvt_pk_bf16_f32 v236, v42, v43
	v_cvt_pk_bf16_f32 v237, v44, v45
	global_store_dwordx2 v[240:241], v[236:237], off offset:128
	ds_read_b64_tr_b16 v[42:43], v34 offset:160
	ds_read_b64_tr_b16 v[44:45], v34 offset:1248
	ds_read_b64_tr_b16 v[46:47], v34 offset:8864
	ds_read_b64_tr_b16 v[48:49], v34 offset:9952
	s_waitcnt lgkmcnt(2)
	v_mfma_f32_16x16x32_bf16 v[42:45], v[42:45], v[12:15], 0
	s_waitcnt lgkmcnt(0)
	v_mfma_f32_16x16x32_bf16 v[42:45], v[46:49], v[8:11], v[42:45]
	ds_read_b64_tr_b16 v[46:47], v34 offset:17568
	ds_read_b64_tr_b16 v[48:49], v34 offset:18656
	s_waitcnt lgkmcnt(0)
	v_mfma_f32_16x16x32_bf16 v[42:45], v[46:49], v[4:7], v[42:45]
	ds_read_b64_tr_b16 v[46:47], v34 offset:26272
	ds_read_b64_tr_b16 v[48:49], v34 offset:27360
	s_waitcnt lgkmcnt(0)
	v_mfma_f32_16x16x32_bf16 v[42:45], v[46:49], v[0:3], v[42:45]
	s_nop 7
	v_cvt_pk_bf16_f32 v236, v42, v43
	v_cvt_pk_bf16_f32 v237, v44, v45
	global_store_dwordx2 v[240:241], v[236:237], off offset:160
	ds_read_b64_tr_b16 v[42:43], v34 offset:192
	ds_read_b64_tr_b16 v[44:45], v34 offset:1280
	ds_read_b64_tr_b16 v[46:47], v34 offset:8896
	ds_read_b64_tr_b16 v[48:49], v34 offset:9984
	s_waitcnt lgkmcnt(2)
	v_mfma_f32_16x16x32_bf16 v[42:45], v[42:45], v[12:15], 0
	s_waitcnt lgkmcnt(0)
	v_mfma_f32_16x16x32_bf16 v[42:45], v[46:49], v[8:11], v[42:45]
	ds_read_b64_tr_b16 v[46:47], v34 offset:17600
	ds_read_b64_tr_b16 v[48:49], v34 offset:18688
	s_waitcnt lgkmcnt(0)
	v_mfma_f32_16x16x32_bf16 v[42:45], v[46:49], v[4:7], v[42:45]
	ds_read_b64_tr_b16 v[46:47], v34 offset:26304
	ds_read_b64_tr_b16 v[48:49], v34 offset:27392
	s_waitcnt lgkmcnt(0)
	v_mfma_f32_16x16x32_bf16 v[42:45], v[46:49], v[0:3], v[42:45]
	s_nop 7
	v_cvt_pk_bf16_f32 v236, v42, v43
	v_cvt_pk_bf16_f32 v237, v44, v45
	global_store_dwordx2 v[240:241], v[236:237], off offset:192
	ds_read_b64_tr_b16 v[42:43], v34 offset:224
	ds_read_b64_tr_b16 v[44:45], v34 offset:1312
	s_waitcnt lgkmcnt(0)
	v_mfma_f32_16x16x32_bf16 v[12:15], v[42:45], v[12:15], 0
	ds_read_b64_tr_b16 v[42:43], v34 offset:8928
	ds_read_b64_tr_b16 v[44:45], v34 offset:10016
	s_waitcnt lgkmcnt(0)
	v_mfma_f32_16x16x32_bf16 v[8:11], v[42:45], v[8:11], v[12:15]
	s_nop 3
	ds_read_b64_tr_b16 v[12:13], v34 offset:17632
	ds_read_b64_tr_b16 v[14:15], v34 offset:18720
	s_waitcnt lgkmcnt(0)
	v_mfma_f32_16x16x32_bf16 v[4:7], v[12:15], v[4:7], v[8:11]
	s_nop 2
	ds_read_b64_tr_b16 v[8:9], v34 offset:26336
	ds_read_b64_tr_b16 v[10:11], v34 offset:27424
	s_waitcnt lgkmcnt(0)
	v_mfma_f32_16x16x32_bf16 v[0:3], v[8:11], v[0:3], v[4:7]
	s_nop 7
	v_cvt_pk_bf16_f32 v236, v0, v1
	v_cvt_pk_bf16_f32 v237, v2, v3
	global_store_dwordx2 v[240:241], v[236:237], off offset:224
	s_waitcnt lgkmcnt(0)
	s_barrier
	s_cbranch_scc1 .LBB0_278
